# w_uq GEMM epilogue: rotary prefetch extended to the last row group (all 16 column blocks now read preloaded cos/sin)
# speedup vs baseline: 1.0169x; 1.0064x over previous
;   DI void operator()(const f32x4 (&acc)[2][2][4][2], const pg8::Unit& u, int wr, int wc, int fr, int fq) const {
;     const int row0 = u.pm * 256 + wr * 64 + fr, colb = u.pn * 256 + wc * 32 + 8 * fq;
; #pragma unroll
;     for (int ai = 0; ai < 2; ++ai)
; #pragma unroll
;       for (int m = 0; m < 4; ++m) {
;         const int row = row0 + ai * 128 + m * 16;
; #pragma unroll
;         for (int bj = 0; bj < 2; ++bj) {
;           const int col = colb + bj * 128;
;           f32x4 v0 = acc[ai][bj][m][0] * sc, v1 = acc[ai][bj][m][1] * sc;
;           u16* dst = nullptr;
;           if (MODE == 0) { if (col < N) dst = d0 + (size_t)row * ld0 + (col + coff2 + ((col < csplit) ? (coff1 - coff2) : 0)); }
;           else if (MODE == 1) {
;             const int oc = col + coff2 + ((col < csplit) ? (coff1 - coff2) : 0);
;             if (col < N) {
;               if (oc < 2048) dst = d0 + (size_t)row * 2048 + oc;
;               else if (oc < 2112) { rot(v0, v1, row, oc); dst = d2 + (size_t)row * 64 + (oc - 2048); }
;               else dst = d1 + (size_t)row * 4096 + (oc - 2112);
;             }
;           } else if (MODE == 3) {
;             if (col < N) { const bool lo = col < csplit; u16* bp = lo ? d0 : d1; const int ldd = lo ? 2048 : 4096, oc = lo ? col : col + (coff2 - 2112); dst = bp + (size_t)row * ldd + oc + (lo ? coff1 : 0); }
;           } else {
;             if (((col >> 6) % 3) == 2) rot(v0, v1, row, col);
;             dst = d0 + (size_t)row * 3072 + col;
;           }
;           if (dst) { u32x4 w = {pk2(v0[0], v0[1]), pk2(v0[2], v0[3]), pk2(v1[0], v1[1]), pk2(v1[2], v1[3])}; *(u32x4*)dst = w; }
.LBB0_1107:
	s_or_b64 exec, exec, s[16:17]
	v_cvt_pk_bf16_f32 v8, v8, v9
	v_cvt_pk_bf16_f32 v9, v14, v15
	v_cvt_pk_bf16_f32 v10, v10, v11
	v_cvt_pk_bf16_f32 v11, v12, v13
	global_store_dwordx4 v[6:7], v[8:11], off offset:256
	v_add_u32_e32 v6, 0x80, v16
	v_lshlrev_b32_e32 v0, 5, v6
	v_and_b32_e32 v0, 0xf9e0, v0
	v_pk_mul_f32 v[14:15], v[88:89], s[58:59] op_sel_hi:[1,0]
	v_pk_mul_f32 v[8:9], v[86:87], s[58:59] op_sel_hi:[1,0]
	v_pk_mul_f32 v[12:13], v[84:85], s[58:59] op_sel_hi:[1,0]
	v_pk_mul_f32 v[10:11], v[82:83], s[58:59] op_sel_hi:[1,0]
	s_and_b64 vcc, exec, s[12:13]
	v_lshlrev_b32_e32 v0, 3, v0
	v_mov_b32_e32 v238, v2
	v_mov_b32_e32 v239, 0
	v_add_u32_e32 v236, 128, v16
	v_lshlrev_b32_e32 v236, 5, v236
	v_and_b32_e32 v236, 0xffe0, v236
	v_lshlrev_b32_e32 v236, 3, v236
	v_mov_b32_e32 v237, 0
	v_lshl_add_u64 v[236:237], s[52:53], 0, v[236:237]
	v_lshl_add_u64 v[236:237], v[236:237], 0, v[238:239]
	global_load_dwordx4 v[186:189], v[236:237], off offset:16
	global_load_dwordx4 v[190:193], v[236:237], off
	v_add_u32_e32 v236, 144, v16
	v_lshlrev_b32_e32 v236, 5, v236
	v_and_b32_e32 v236, 0xffe0, v236
	v_lshlrev_b32_e32 v236, 3, v236
	v_mov_b32_e32 v237, 0
	v_lshl_add_u64 v[236:237], s[52:53], 0, v[236:237]
	v_lshl_add_u64 v[236:237], v[236:237], 0, v[238:239]
	global_load_dwordx4 v[194:197], v[236:237], off offset:16
	global_load_dwordx4 v[198:201], v[236:237], off
	v_add_u32_e32 v236, 160, v16
	v_lshlrev_b32_e32 v236, 5, v236
	v_and_b32_e32 v236, 0xffe0, v236
	v_lshlrev_b32_e32 v236, 3, v236
	v_mov_b32_e32 v237, 0
	v_lshl_add_u64 v[236:237], s[52:53], 0, v[236:237]
	v_lshl_add_u64 v[236:237], v[236:237], 0, v[238:239]
	global_load_dwordx4 v[202:205], v[236:237], off offset:16
	global_load_dwordx4 v[206:209], v[236:237], off
	v_add_u32_e32 v236, 176, v16
	v_lshlrev_b32_e32 v236, 5, v236
	v_and_b32_e32 v236, 0xffe0, v236
	v_lshlrev_b32_e32 v236, 3, v236
	v_mov_b32_e32 v237, 0
	v_lshl_add_u64 v[236:237], s[52:53], 0, v[236:237]
	v_lshl_add_u64 v[236:237], v[236:237], 0, v[238:239]
	global_load_dwordx4 v[210:213], v[236:237], off offset:16
	global_load_dwordx4 v[214:217], v[236:237], off
	s_waitcnt vmcnt(0)
	s_cbranch_vccnz .LBB0_1109
	v_mov_b32_e32 v3, v1
	v_mov_b32_e32 v18, v186
	v_mov_b32_e32 v19, v187
	v_mov_b32_e32 v20, v188
	v_mov_b32_e32 v21, v189
	v_mov_b32_e32 v22, v190
	v_mov_b32_e32 v23, v191
	v_mov_b32_e32 v24, v192
	v_mov_b32_e32 v25, v193
	v_pk_mul_f32 v[86:87], v[10:11], v[18:19] op_sel:[1,1] op_sel_hi:[0,1]
	v_pk_mul_f32 v[84:85], v[8:9], v[22:23] op_sel:[1,1] op_sel_hi:[0,1]
	v_pk_mul_f32 v[82:83], v[8:9], v[22:23]
	v_pk_fma_f32 v[8:9], v[8:9], v[22:23], v[84:85] op_sel_hi:[1,0,1]
	s_nop 0
	v_mul_f32_e32 v8, v15, v25
	v_pk_fma_f32 v[22:23], v[14:15], v[24:25], v[8:9] op_sel_hi:[1,1,0] neg_lo:[0,0,1] neg_hi:[0,0,1]
	v_mul_f32_e32 v8, v14, v25
	v_pk_fma_f32 v[24:25], v[14:15], v[24:25], v[8:9] op_sel:[1,0,0] op_sel_hi:[0,1,0]
	v_mul_f32_e32 v8, v13, v21
	v_pk_mul_f32 v[14:15], v[10:11], v[18:19]
	v_pk_fma_f32 v[10:11], v[10:11], v[18:19], v[86:87] op_sel_hi:[1,0,1]
	v_pk_fma_f32 v[18:19], v[12:13], v[20:21], v[8:9] op_sel_hi:[1,1,0] neg_lo:[0,0,1] neg_hi:[0,0,1]
	v_mul_f32_e32 v8, v12, v21
	v_pk_fma_f32 v[20:21], v[12:13], v[20:21], v[8:9] op_sel:[1,0,0] op_sel_hi:[0,1,0]
	v_sub_f32_e32 v10, v14, v86
	v_sub_f32_e32 v8, v82, v84
	v_mov_b32_e32 v12, v18
	v_mov_b32_e32 v13, v20
	v_mov_b32_e32 v14, v22
	v_mov_b32_e32 v15, v24

;   DI void operator()(const f32x4 (&acc)[2][2][4][2], const pg8::Unit& u, int wr, int wc, int fr, int fq) const {
;     const int row0 = u.pm * 256 + wr * 64 + fr, colb = u.pn * 256 + wc * 32 + 8 * fq;
; #pragma unroll
;     for (int ai = 0; ai < 2; ++ai)
; #pragma unroll
;       for (int m = 0; m < 4; ++m) {
;         const int row = row0 + ai * 128 + m * 16;
; #pragma unroll
;         for (int bj = 0; bj < 2; ++bj) {
;           const int col = colb + bj * 128;
;           f32x4 v0 = acc[ai][bj][m][0] * sc, v1 = acc[ai][bj][m][1] * sc;
;           u16* dst = nullptr;
;           if (MODE == 0) { if (col < N) dst = d0 + (size_t)row * ld0 + (col + coff2 + ((col < csplit) ? (coff1 - coff2) : 0)); }
;           else if (MODE == 1) {
;             const int oc = col + coff2 + ((col < csplit) ? (coff1 - coff2) : 0);
;             if (col < N) {
;               if (oc < 2048) dst = d0 + (size_t)row * 2048 + oc;
;               else if (oc < 2112) { rot(v0, v1, row, oc); dst = d2 + (size_t)row * 64 + (oc - 2048); }
;               else dst = d1 + (size_t)row * 4096 + (oc - 2112);
;             }
;           } else if (MODE == 3) {
;             if (col < N) { const bool lo = col < csplit; u16* bp = lo ? d0 : d1; const int ldd = lo ? 2048 : 4096, oc = lo ? col : col + (coff2 - 2112); dst = bp + (size_t)row * ldd + oc + (lo ? coff1 : 0); }
;           } else {
;             if (((col >> 6) % 3) == 2) rot(v0, v1, row, col);
;             dst = d0 + (size_t)row * 3072 + col;
;           }
;           if (dst) { u32x4 w = {pk2(v0[0], v0[1]), pk2(v0[2], v0[3]), pk2(v1[0], v1[1]), pk2(v1[2], v1[3])}; *(u32x4*)dst = w; }
.LBB0_1119:
	s_or_b64 exec, exec, s[16:17]
	v_cvt_pk_bf16_f32 v8, v8, v9
	v_cvt_pk_bf16_f32 v9, v14, v15
	v_cvt_pk_bf16_f32 v10, v10, v11
	v_cvt_pk_bf16_f32 v11, v12, v13
	global_store_dwordx4 v[6:7], v[8:11], off offset:256
	v_add_u32_e32 v14, 0xb0, v16
	v_lshlrev_b32_e32 v0, 5, v14
	v_and_b32_e32 v0, 0xffe0, v0
	v_pk_mul_f32 v[12:13], v[40:41], s[58:59] op_sel_hi:[1,0]
	v_pk_mul_f32 v[6:7], v[38:39], s[58:59] op_sel_hi:[1,0]
	v_pk_mul_f32 v[10:11], v[36:37], s[58:59] op_sel_hi:[1,0]
	v_pk_mul_f32 v[8:9], v[34:35], s[58:59] op_sel_hi:[1,0]
	s_and_b64 vcc, exec, s[12:13]
	v_lshlrev_b32_e32 v0, 3, v0
	s_cbranch_vccnz .LBB0_1121
	v_mov_b32_e32 v3, v1
	v_mov_b32_e32 v16, v210
	v_mov_b32_e32 v17, v211
	v_mov_b32_e32 v18, v212
	v_mov_b32_e32 v19, v213
	v_mov_b32_e32 v20, v214
	v_mov_b32_e32 v21, v215
	v_mov_b32_e32 v22, v216
	v_mov_b32_e32 v23, v217
	v_pk_mul_f32 v[36:37], v[8:9], v[16:17] op_sel:[1,1] op_sel_hi:[0,1]
	v_pk_mul_f32 v[34:35], v[6:7], v[20:21] op_sel:[1,1] op_sel_hi:[0,1]
	v_pk_mul_f32 v[24:25], v[6:7], v[20:21]
	v_pk_fma_f32 v[6:7], v[6:7], v[20:21], v[34:35] op_sel_hi:[1,0,1]
	s_nop 0
	v_mul_f32_e32 v6, v13, v23
	v_pk_fma_f32 v[20:21], v[12:13], v[22:23], v[6:7] op_sel_hi:[1,1,0] neg_lo:[0,0,1] neg_hi:[0,0,1]
	v_mul_f32_e32 v6, v12, v23
	v_pk_fma_f32 v[22:23], v[12:13], v[22:23], v[6:7] op_sel:[1,0,0] op_sel_hi:[0,1,0]
	v_mul_f32_e32 v6, v11, v19
	v_pk_mul_f32 v[12:13], v[8:9], v[16:17]
	v_pk_fma_f32 v[8:9], v[8:9], v[16:17], v[36:37] op_sel_hi:[1,0,1]
	v_pk_fma_f32 v[16:17], v[10:11], v[18:19], v[6:7] op_sel_hi:[1,1,0] neg_lo:[0,0,1] neg_hi:[0,0,1]
	v_mul_f32_e32 v6, v10, v19
	v_pk_fma_f32 v[18:19], v[10:11], v[18:19], v[6:7] op_sel:[1,0,0] op_sel_hi:[0,1,0]
	v_sub_f32_e32 v8, v12, v36
	v_sub_f32_e32 v6, v24, v34
	v_mov_b32_e32 v10, v16
	v_mov_b32_e32 v11, v18
	v_mov_b32_e32 v12, v20
	v_mov_b32_e32 v13, v22
.LBB0_1121:
	v_mov_b64_e32 v[16:17], s[74:75]
	s_movk_i32 s12, 0x1800
	v_mad_i64_i32 v[14:15], s[12:13], v14, s12, v[16:17]
	v_lshl_add_u64 v[4:5], v[4:5], 1, v[14:15]
	v_cvt_pk_bf16_f32 v6, v6, v7
	v_cvt_pk_bf16_f32 v7, v12, v13
	v_cvt_pk_bf16_f32 v8, v8, v9
	v_cvt_pk_bf16_f32 v9, v10, v11
	global_store_dwordx4 v[4:5], v[6:9], off
	v_pk_mul_f32 v[12:13], v[32:33], s[58:59] op_sel_hi:[1,0]
	v_pk_mul_f32 v[10:11], v[28:29], s[58:59] op_sel_hi:[1,0]
	v_pk_mul_f32 v[6:7], v[30:31], s[58:59] op_sel_hi:[1,0]
	v_pk_mul_f32 v[8:9], v[26:27], s[58:59] op_sel_hi:[1,0]
	s_and_saveexec_b64 s[12:13], s[10:11]
	s_cbranch_execz .LBB0_1082
	v_mov_b32_e32 v3, v1
	v_mov_b32_e32 v14, v210
	v_mov_b32_e32 v15, v211
	v_mov_b32_e32 v16, v212
	v_mov_b32_e32 v17, v213
	v_mov_b32_e32 v18, v214
	v_mov_b32_e32 v19, v215
	v_mov_b32_e32 v20, v216
	v_mov_b32_e32 v21, v217
	v_pk_mul_f32 v[24:25], v[8:9], v[14:15] op_sel:[1,1] op_sel_hi:[0,1]
	v_pk_mul_f32 v[22:23], v[6:7], v[18:19] op_sel:[1,1] op_sel_hi:[0,1]
	v_mul_f32_e32 v0, v13, v21
	v_pk_mul_f32 v[2:3], v[6:7], v[18:19]
	v_pk_fma_f32 v[6:7], v[6:7], v[18:19], v[22:23] op_sel_hi:[1,0,1]
	v_pk_fma_f32 v[18:19], v[12:13], v[20:21], v[0:1] op_sel_hi:[1,1,0] neg_lo:[0,0,1] neg_hi:[0,0,1]
	v_mul_f32_e32 v0, v12, v21
	v_pk_fma_f32 v[20:21], v[12:13], v[20:21], v[0:1] op_sel:[1,0,0] op_sel_hi:[0,1,0]
	v_mul_f32_e32 v0, v11, v17
	v_pk_mul_f32 v[12:13], v[8:9], v[14:15]
	v_pk_fma_f32 v[8:9], v[8:9], v[14:15], v[24:25] op_sel_hi:[1,0,1]
	v_pk_fma_f32 v[14:15], v[10:11], v[16:17], v[0:1] op_sel_hi:[1,1,0] neg_lo:[0,0,1] neg_hi:[0,0,1]
	v_mul_f32_e32 v0, v10, v17
	v_pk_fma_f32 v[16:17], v[10:11], v[16:17], v[0:1] op_sel:[1,0,0] op_sel_hi:[0,1,0]
	v_sub_f32_e32 v8, v12, v24
	v_sub_f32_e32 v6, v2, v22
	v_mov_b32_e32 v10, v14
	v_mov_b32_e32 v11, v16
	v_mov_b32_e32 v12, v18
	v_mov_b32_e32 v13, v20
	s_branch .LBB0_1082
